# static s_setprio 1 for waves 4-7 in both hand-pipelined attention loops (MLA loop now also replaced); DFT tiles published with write-through stores instead of an L2 write-back fence
# speedup vs baseline: 1.1071x; 1.0220x over previous
; template <int DQK, bool STATIC>
; DI void attn_item8(const bf16_t* __restrict__ Q, const bf16_t* __restrict__ Kp, const bf16_t* __restrict__ Vt, int nkeys, char* lds,
;                   const bf16_t* __restrict__ Pg, bf16_t* __restrict__ Yg  , float mfix) {
;     ...
;   f32x16 o[2];
; #pragma unroll
;   for (int d = 0; d < 2; ++d)
; #pragma unroll
;     for (int e = 0; e < 16; ++e) o[d][e] = 0.f;
;   float m_run = STATIC ? mfix : -1e30f, l_run = 0.f;
;   u32x4 rk[NKC], rv[1];
;   int koffg[NKC], koffl[NKC];
; #pragma unroll
;   for (int i = 0; i < NKC; ++i) { const int c = tid + 512 * i; const int key = c / KCH, part = c % KCH; koffg[i] = (c < 64 * KCH) ? c * 8 : 0; koffl[i] = (c < 64 * KCH) ? key * KSTR + part * 16 : -1; }
;   const int vdv0 = tid >> 3, vpart = tid & 7;
;   const bf16_t* vg = Vt + (size_t)vdv0 * T + vpart * 8;
;   const int voffl = KBUF + vdv0 * VSTR + vpart * 16;
;   const int nt = nkeys >> 6;
; #pragma unroll
;   for (int i = 0; i < NKC; ++i) rk[i] = *(const u32x4*)(Kp + koffg[i]);
; #pragma unroll
;   for (int i = 0; i < 1; ++i) rv[i] = *(const u32x4*)(vg + (size_t)i * 32 * T);
; #pragma unroll
;   for (int i = 0; i < NKC; ++i) if (koffl[i] >= 0) *(u32x4*)(lds + koffl[i]) = rk[i];
; #pragma unroll
;   for (int i = 0; i < 1; ++i) { u32x2 a = {rv[i].x, rv[i].y}, b = {rv[i].z, rv[i].w}; *(u32x2*)(lds + voffl + i * 32 * VSTR) = a; *(u32x2*)(lds + voffl + i * 32 * VSTR + 8) = b; }
;   {
; #pragma unroll
;     for (int i = 0; i < NKC; ++i) rk[i] = *(const u32x4*)(Kp + (size_t)64 * DQK + koffg[i]);
;     rv[0] = *(const u32x4*)(vg + 64);
; #pragma unroll
;     for (int i = 0; i < NKC; ++i) if (koffl[i] >= 0) *(u32x4*)(lds + BUF + koffl[i]) = rk[i];
;     { u32x2 a = {rv[0].x, rv[0].y}, b = {rv[0].z, rv[0].w}; *(u32x2*)(lds + BUF + voffl) = a; *(u32x2*)(lds + BUF + voffl + 8) = b; }
;   }
;   __syncthreads();
.LBB0_43:
	s_or_b64 exec, exec, s[18:19]
	v_and_b32_e32 v34, 31, v40
	v_add_u32_e32 v35, 0x6a00, v42
	v_mov_b32_e32 v215, 0
	v_lshlrev_b32_e32 v128, 3, v187
	s_waitcnt vmcnt(0) lgkmcnt(0)
	ds_write2_b64 v35, v[118:119], v[120:121] offset1:1
	v_mul_u32_u24_e32 v129, 0x90, v34
	v_mul_u32_u24_e32 v130, 0x88, v34
	s_mov_b32 s49, 0
	v_mov_b32_e32 v50, 0
	v_mov_b32_e32 v51, v215
	v_mov_b32_e32 v52, v215
	v_mov_b32_e32 v53, v215
	v_mov_b32_e32 v54, v215
	v_mov_b32_e32 v55, v215
	v_mov_b32_e32 v56, v215
	v_mov_b32_e32 v57, v215
	v_mov_b32_e32 v58, v215
	v_mov_b32_e32 v59, v215
	v_mov_b32_e32 v60, v215
	v_mov_b32_e32 v61, v215
	v_mov_b32_e32 v62, v215
	v_mov_b32_e32 v63, v215
	v_mov_b32_e32 v64, v215
	v_mov_b32_e32 v65, v215
	v_mov_b32_e32 v34, v215
	v_mov_b32_e32 v35, v215
	v_mov_b32_e32 v36, v215
	v_mov_b32_e32 v37, v215
	v_mov_b32_e32 v38, v215
	v_mov_b32_e32 v39, v215
	v_mov_b32_e32 v40, v215
	v_mov_b32_e32 v41, v215
	v_mov_b32_e32 v42, v215
	v_mov_b32_e32 v43, v215
	v_mov_b32_e32 v44, v215
	v_mov_b32_e32 v45, v215
	v_mov_b32_e32 v46, v215
	v_mov_b32_e32 v47, v215
	v_mov_b32_e32 v48, v215
	v_mov_b32_e32 v49, v215
	v_readfirstlane_b32 s74, v196
	s_cmpk_ge_u32 s74, 0x100
	s_cbranch_scc0 .Lab_noprio
	s_setprio 1
.Lab_noprio:
	s_waitcnt lgkmcnt(0)
	s_barrier
	s_branch .LBB0_45

; DI unsigned cvtpk(float lo, float hi) { f32x2 v = {lo, hi}; bf16x2_t b = __builtin_convertvector(v, bf16x2_t); return __builtin_bit_cast(unsigned, b); }
; #define MFMA32(a, b, c) __builtin_amdgcn_mfma_f32_32x32x16_bf16((a), (b), (c), 0, 0, 0)
; template <int DQK, bool STATIC>
; DI void attn_item8(const bf16_t* __restrict__ Q, const bf16_t* __restrict__ Kp, const bf16_t* __restrict__ Vt, int nkeys, char* lds,
;                   const bf16_t* __restrict__ Pg, bf16_t* __restrict__ Yg  , float mfix) {
;     ...
;     {
;       float ps = 0.f;
; #pragma unroll
;       for (int e = 0; e < 16; ++e) { float p = STATIC ? __builtin_amdgcn_exp2f(s1[e]) : __builtin_amdgcn_exp2f(s1[e] - m_run); s1[e] = p; ps += p; }
;       l_run += ps;
;     }
; #pragma unroll
;     for (int s2 = 0; s2 < 2; ++s2) {
;       u32x4 pw = {cvtpk(s1[8 * s2], s1[8 * s2 + 1]), cvtpk(s1[8 * s2 + 2], s1[8 * s2 + 3]), cvtpk(s1[8 * s2 + 4], s1[8 * s2 + 5]), cvtpk(s1[8 * s2 + 6], s1[8 * s2 + 7])};
;       bf16x8 pf = __builtin_bit_cast(bf16x8, pw);
; #pragma unroll
;       for (int d = 0; d < 2; ++d) o[d] = MFMA32(__builtin_bit_cast(bf16x8, vw[1][s2][d]), pf, o[d]);
;     }
;     if (more) {
;       char* nxt = nxtp + sub * BUF;
; #pragma unroll
;       for (int i = 0; i < NKC; ++i) if (koffl[i] >= 0) *(u32x4*)(nxt + koffl[i]) = rk[i];
; #pragma unroll
;       for (int i = 0; i < 1; ++i) { u32x2 a = {rv[i].x, rv[i].y}, b = {rv[i].z, rv[i].w}; *(u32x2*)(nxt + voffl + i * 32 * VSTR) = a; *(u32x2*)(nxt + voffl + i * 32 * VSTR + 8) = b; }
;     }
;    }
;    __syncthreads();
;   }
;   const float lt = l_run + __shfl_xor(l_run, 32);
.Lab_nostage1:
.Lab_pairend:
	s_cmp_eq_u32 s49, s65
	s_waitcnt lgkmcnt(0)
	s_barrier
	s_cbranch_scc0 .LBB0_45
	v_add_f32_e32 v137, v66, v68
	v_add_f32_e32 v138, v67, v69
	v_add_f32_e32 v137, v70, v137
	v_add_f32_e32 v138, v71, v138
	v_add_f32_e32 v137, v72, v137
	v_add_f32_e32 v138, v73, v138
	v_add_f32_e32 v137, v74, v137
	v_add_f32_e32 v138, v75, v138
	v_add_f32_e32 v137, v76, v137
	v_add_f32_e32 v138, v77, v138
	v_add_f32_e32 v137, v78, v137
	v_add_f32_e32 v138, v79, v138
	v_add_f32_e32 v137, v80, v137
	v_add_f32_e32 v138, v81, v138
	v_add_f32_e32 v137, v137, v138
	v_add_f32_e32 v215, v215, v137
	s_nop 7
	s_setprio 0

; template <int DQK, bool STATIC>
; DI void attn_item8(const bf16_t* __restrict__ Q, const bf16_t* __restrict__ Kp, const bf16_t* __restrict__ Vt, int nkeys, char* lds,
;                   const bf16_t* __restrict__ Pg, bf16_t* __restrict__ Yg  , float mfix) {
;     ...
;   f32x16 o[2];
; #pragma unroll
;   for (int d = 0; d < 2; ++d)
; #pragma unroll
;     for (int e = 0; e < 16; ++e) o[d][e] = 0.f;
;   float m_run = STATIC ? mfix : -1e30f, l_run = 0.f;
;   u32x4 rk[NKC], rv[1];
;   int koffg[NKC], koffl[NKC];
; #pragma unroll
;   for (int i = 0; i < NKC; ++i) { const int c = tid + 512 * i; const int key = c / KCH, part = c % KCH; koffg[i] = (c < 64 * KCH) ? c * 8 : 0; koffl[i] = (c < 64 * KCH) ? key * KSTR + part * 16 : -1; }
;   const int vdv0 = tid >> 3, vpart = tid & 7;
;   const bf16_t* vg = Vt + (size_t)vdv0 * T + vpart * 8;
;   const int voffl = KBUF + vdv0 * VSTR + vpart * 16;
;   const int nt = nkeys >> 6;
; #pragma unroll
;   for (int i = 0; i < NKC; ++i) rk[i] = *(const u32x4*)(Kp + koffg[i]);
; #pragma unroll
;   for (int i = 0; i < 1; ++i) rv[i] = *(const u32x4*)(vg + (size_t)i * 32 * T);
; #pragma unroll
;   for (int i = 0; i < NKC; ++i) if (koffl[i] >= 0) *(u32x4*)(lds + koffl[i]) = rk[i];
; #pragma unroll
;   for (int i = 0; i < 1; ++i) { u32x2 a = {rv[i].x, rv[i].y}, b = {rv[i].z, rv[i].w}; *(u32x2*)(lds + voffl + i * 32 * VSTR) = a; *(u32x2*)(lds + voffl + i * 32 * VSTR + 8) = b; }
;   {
; #pragma unroll
;     for (int i = 0; i < NKC; ++i) rk[i] = *(const u32x4*)(Kp + (size_t)64 * DQK + koffg[i]);
;     rv[0] = *(const u32x4*)(vg + 64);
; #pragma unroll
;     for (int i = 0; i < NKC; ++i) if (koffl[i] >= 0) *(u32x4*)(lds + BUF + koffl[i]) = rk[i];
;     { u32x2 a = {rv[0].x, rv[0].y}, b = {rv[0].z, rv[0].w}; *(u32x2*)(lds + BUF + voffl) = a; *(u32x2*)(lds + BUF + voffl + 8) = b; }
;   }
;   __syncthreads();
.LBB0_85:
	s_or_b64 exec, exec, s[18:19]
	v_and_b32_e32 v35, 31, v42
	v_add_u32_e32 v34, 0x8a00, v34
	v_mov_b32_e32 v215, 0
	v_ashrrev_i32_e32 v189, 31, v188
	v_lshlrev_b32_e32 v143, 3, v187
	s_waitcnt vmcnt(0) lgkmcnt(0)
	ds_write2_b64 v34, v[130:131], v[132:133] offset1:1
	v_mul_u32_u24_e32 v144, 0xd0, v35
	v_mul_u32_u24_e32 v145, 0x88, v35
	s_mov_b32 s2, 0
	v_mov_b32_e32 v50, 0
	v_mov_b32_e32 v51, v215
	v_mov_b32_e32 v52, v215
	v_mov_b32_e32 v53, v215
	v_mov_b32_e32 v54, v215
	v_mov_b32_e32 v55, v215
	v_mov_b32_e32 v56, v215
	v_mov_b32_e32 v57, v215
	v_mov_b32_e32 v58, v215
	v_mov_b32_e32 v59, v215
	v_mov_b32_e32 v60, v215
	v_mov_b32_e32 v61, v215
	v_mov_b32_e32 v62, v215
	v_mov_b32_e32 v63, v215
	v_mov_b32_e32 v64, v215
	v_mov_b32_e32 v65, v215
	v_mov_b32_e32 v34, v215
	v_mov_b32_e32 v35, v215
	v_mov_b32_e32 v36, v215
	v_mov_b32_e32 v37, v215
	v_mov_b32_e32 v38, v215
	v_mov_b32_e32 v39, v215
	v_mov_b32_e32 v40, v215
	v_mov_b32_e32 v41, v215
	v_mov_b32_e32 v42, v215
	v_mov_b32_e32 v43, v215
	v_mov_b32_e32 v44, v215
	v_mov_b32_e32 v45, v215
	v_mov_b32_e32 v46, v215
	v_mov_b32_e32 v47, v215
	v_mov_b32_e32 v48, v215
	v_mov_b32_e32 v49, v215
	v_readfirstlane_b32 s74, v196
	s_cmpk_ge_u32 s74, 0x100
	s_cbranch_scc0 .Laa_noprio
	s_setprio 1

; #define MFMA32(a, b, c) __builtin_amdgcn_mfma_f32_32x32x16_bf16((a), (b), (c), 0, 0, 0)
; template <int DQK, bool STATIC>
; DI void attn_item8(const bf16_t* __restrict__ Q, const bf16_t* __restrict__ Kp, const bf16_t* __restrict__ Vt, int nkeys, char* lds,
;                   const bf16_t* __restrict__ Pg, bf16_t* __restrict__ Yg  , float mfix) {
;     ...
;     if (more) {
; #pragma unroll
;       for (int i = 0; i < NKC; ++i) rk[i] = *(const u32x4*)(Kp + (size_t)(j + 1) * 64 * DQK + koffg[i]);
; #pragma unroll
;       for (int i = 0; i < 1; ++i) rv[i] = *(const u32x4*)(vg + (size_t)i * 32 * T + (j + 1) * 64);
;     }
;     f32x16 s0, s1;
;     bf16x8 kf[2][NQS];
; #pragma unroll
;     for (int kb = 0; kb < 2; ++kb)
; #pragma unroll
;       for (int ks = 0; ks < NQS; ++ks) kf[kb][ks] = *(const bf16x8*)(cur + (32 * kb + l31) * KSTR + (2 * ks + h) * 16);
;     u32x4 vw[2][2][2];
; #pragma unroll
;     for (int kb = 0; kb < 2; ++kb)
; #pragma unroll
;       for (int s2 = 0; s2 < 2; ++s2)
; #pragma unroll
;         for (int d = 0; d < 2; ++d) {
;           const char* vp = cur + KBUF + (32 * d + l31) * VSTR + (32 * kb + 16 * s2 + 4 * h) * 2;
;           u32x2 v0 = *(const u32x2*)vp, v1 = *(const u32x2*)(vp + 16);
;           u32x4 t4 = {v0.x, v0.y, v1.x, v1.y}; vw[kb][s2][d] = t4;
;         }
; #pragma unroll
;     for (int e = 0; e < 16; ++e) { s0[e] = STATIC ? -mfix : 0.f; s1[e] = STATIC ? -mfix : 0.f; }
; #pragma unroll
;     for (int ks = 0; ks < NQS; ++ks) s0 = MFMA32(kf[0][ks], qf[ks], s0);
;     if (!STATIC) {
;       float mx = s0[0];
; #pragma unroll
;       for (int e = 1; e < 16; ++e) mx = fmaxf(mx, s0[e]);
;       mx = fmaxf(mx, __shfl_xor(mx, 32));
;       if (!__all(mx <= m_run + 8.f)) {
;         const float m_new = fmaxf(m_run, mx);
;         const float alpha = __builtin_amdgcn_exp2f(m_run - m_new);
;         m_run = m_new; l_run *= alpha;
; #pragma unroll
;         for (int d = 0; d < 2; ++d)
; #pragma unroll
;           for (int e = 0; e < 16; ++e) o[d][e] *= alpha;
;       }
;     }
; #pragma unroll
;     for (int ks = 0; ks < NQS; ++ks) s1 = MFMA32(kf[1][ks], qf[ks], s1);
;     {
;       float ps = 0.f;
; #pragma unroll
;       for (int e = 0; e < 16; ++e) { float p = STATIC ? __builtin_amdgcn_exp2f(s0[e]) : __builtin_amdgcn_exp2f(s0[e] - m_run); s0[e] = p; ps += p; }
;     ...
;     for (int s2 = 0; s2 < 2; ++s2) {
.LBB0_87:
	s_and_b32 s18, s2, 1
	s_mul_i32 s21, s18, 0xac00
	s_xor_b32 s18, s18, 1
	s_mul_i32 s19, s18, 0xac00
	s_add_i32 s2, s2, 1
	s_cmp_eq_u32 s2, 1
	s_cbranch_scc1 .Laa_nodef
	v_add_f32_e32 v192, v66, v68
	v_add_f32_e32 v193, v67, v69
	v_add_f32_e32 v192, v70, v192
	v_add_f32_e32 v193, v71, v193
	v_add_f32_e32 v192, v72, v192
	v_add_f32_e32 v193, v73, v193
	v_add_f32_e32 v192, v74, v192
	v_add_f32_e32 v193, v75, v193
	v_add_f32_e32 v192, v76, v192
	v_add_f32_e32 v193, v77, v193
	v_add_f32_e32 v192, v78, v192
	v_add_f32_e32 v193, v79, v193
	v_add_f32_e32 v192, v80, v192
	v_add_f32_e32 v193, v81, v193
	v_add_f32_e32 v192, v192, v193
	v_add_f32_e32 v215, v215, v192
.Laa_nodef:
	s_cmp_lt_u32 s2, s65
	s_cbranch_scc0 .Laa_noload
	s_lshl_b32 s52, s2, 1
	s_mul_i32 s52, s52, 0x3000
	s_add_u32 s52, s56, s52
	s_addc_u32 s53, s57, 0
	v_lshl_add_u64 v[194:195], v[138:139], 1, s[52:53]
	v_lshl_add_u64 v[248:249], v[134:135], 1, s[52:53]
	global_load_dwordx4 v[122:125], v[194:195], off
	global_load_dwordx4 v[126:129], v[248:249], off
	s_add_u32 s52, s52, 0x3000
	s_addc_u32 s53, s53, 0
	v_lshl_add_u64 v[194:195], v[138:139], 1, s[52:53]
	v_lshl_add_u64 v[248:249], v[134:135], 1, s[52:53]
	global_load_dwordx4 v[146:149], v[194:195], off
	global_load_dwordx4 v[150:153], v[248:249], off
	s_lshl_b32 s74, s2, 8
	s_mov_b32 s75, 0
	v_lshl_add_u64 v[194:195], v[136:137], 0, s[74:75]
	global_load_dwordx4 v[130:133], v[194:195], off
	global_load_dwordx4 v[154:157], v[194:195], off offset:128
.Laa_noload:
	s_add_i32 s18, s21, 0x5600
	v_add3_u32 v158, s21, v0, v144
	v_add3_u32 v184, s21, v143, v145
	v_add_u32_e32 v190, 0x4000, v184
	v_add_u32_e32 v184, 0x3000, v184
	v_add3_u32 v159, s18, v0, v144
	v_add3_u32 v185, s18, v143, v145
	v_add_u32_e32 v191, 0x4000, v185
	v_add_u32_e32 v185, 0x3000, v185
	ds_read_b128 v[216:219], v158 offset:0
	ds_read_b128 v[220:223], v158 offset:32
	ds_read_b128 v[224:227], v158 offset:64
	ds_read_b128 v[228:231], v158 offset:96
	ds_read_b128 v[232:235], v158 offset:128
	ds_read_b128 v[236:239], v158 offset:160
	ds_read_b128 v[160:163], v158 offset:6656
	ds_read_b128 v[164:167], v158 offset:6688
	ds_read_b128 v[168:171], v158 offset:6720
	ds_read_b128 v[172:175], v158 offset:6752
	ds_read_b128 v[176:179], v158 offset:6784
	ds_read_b128 v[180:183], v158 offset:6816
	s_waitcnt lgkmcnt(6)
	v_mfma_f32_32x32x16_bf16 v[82:97], v[216:219], v[118:121], v[18:33]
	v_mfma_f32_32x32x16_bf16 v[82:97], v[220:223], v[98:101], v[82:97]
	v_mfma_f32_32x32x16_bf16 v[82:97], v[224:227], v[102:105], v[82:97]
	v_mfma_f32_32x32x16_bf16 v[82:97], v[228:231], v[106:109], v[82:97]
	v_mfma_f32_32x32x16_bf16 v[82:97], v[232:235], v[110:113], v[82:97]
	v_mfma_f32_32x32x16_bf16 v[82:97], v[236:239], v[114:117], v[82:97]
	s_waitcnt lgkmcnt(0)
	ds_read2_b64 v[216:219], v184 offset0:128 offset1:130
	ds_read2_b64 v[220:223], v190 offset0:160 offset1:162
	ds_read2_b64 v[224:227], v184 offset0:132 offset1:134
	ds_read2_b64 v[228:231], v190 offset0:164 offset1:166
	v_mfma_f32_32x32x16_bf16 v[66:81], v[160:163], v[118:121], v[18:33]
	s_nop 5
	v_exp_f32_e32 v82, v82
	v_exp_f32_e32 v83, v83
	v_mfma_f32_32x32x16_bf16 v[66:81], v[164:167], v[98:101], v[66:81]
	v_exp_f32_e32 v84, v84
	v_exp_f32_e32 v85, v85
	v_exp_f32_e32 v86, v86
	v_mfma_f32_32x32x16_bf16 v[66:81], v[168:171], v[102:105], v[66:81]
	v_exp_f32_e32 v87, v87
	v_exp_f32_e32 v88, v88
	v_exp_f32_e32 v89, v89
	v_mfma_f32_32x32x16_bf16 v[66:81], v[172:175], v[106:109], v[66:81]
	v_exp_f32_e32 v90, v90
	v_exp_f32_e32 v91, v91
	v_exp_f32_e32 v92, v92
	v_mfma_f32_32x32x16_bf16 v[66:81], v[176:179], v[110:113], v[66:81]
	v_exp_f32_e32 v93, v93
	v_exp_f32_e32 v94, v94
	v_exp_f32_e32 v95, v95
	v_mfma_f32_32x32x16_bf16 v[66:81], v[180:183], v[114:117], v[66:81]
	v_exp_f32_e32 v96, v96
	v_exp_f32_e32 v97, v97
	v_cvt_pk_bf16_f32 v240, v82, v83
	v_cvt_pk_bf16_f32 v241, v84, v85
	v_cvt_pk_bf16_f32 v242, v86, v87
	v_cvt_pk_bf16_f32 v243, v88, v89
	v_cvt_pk_bf16_f32 v244, v90, v91
	v_cvt_pk_bf16_f32 v245, v92, v93
	v_cvt_pk_bf16_f32 v246, v94, v95
	v_cvt_pk_bf16_f32 v247, v96, v97
	s_waitcnt lgkmcnt(0)
	ds_read2_b64 v[160:163], v184 offset0:136 offset1:138
	ds_read2_b64 v[164:167], v190 offset0:168 offset1:170
	ds_read2_b64 v[168:171], v184 offset0:140 offset1:142
	ds_read2_b64 v[172:175], v190 offset0:172 offset1:174
	v_mfma_f32_32x32x16_bf16 v[50:65], v[216:219], v[240:243], v[50:65]
	v_exp_f32_e32 v66, v66
	v_exp_f32_e32 v67, v67
	v_exp_f32_e32 v68, v68
	v_exp_f32_e32 v69, v69
	v_mfma_f32_32x32x16_bf16 v[34:49], v[220:223], v[240:243], v[34:49]
	v_exp_f32_e32 v70, v70
	v_exp_f32_e32 v71, v71
	v_exp_f32_e32 v72, v72
	v_exp_f32_e32 v73, v73
	v_mfma_f32_32x32x16_bf16 v[50:65], v[224:227], v[244:247], v[50:65]
	v_exp_f32_e32 v74, v74
	v_exp_f32_e32 v75, v75
	v_exp_f32_e32 v76, v76
	v_exp_f32_e32 v77, v77
	v_mfma_f32_32x32x16_bf16 v[34:49], v[228:231], v[244:247], v[34:49]
	v_exp_f32_e32 v78, v78
	v_exp_f32_e32 v79, v79
	v_exp_f32_e32 v80, v80
	v_exp_f32_e32 v81, v81
	v_cvt_pk_bf16_f32 v240, v66, v67
	v_cvt_pk_bf16_f32 v241, v68, v69
	v_cvt_pk_bf16_f32 v242, v70, v71
	v_cvt_pk_bf16_f32 v243, v72, v73
	v_cvt_pk_bf16_f32 v244, v74, v75
	v_cvt_pk_bf16_f32 v245, v76, v77
	v_cvt_pk_bf16_f32 v246, v78, v79
	v_cvt_pk_bf16_f32 v247, v80, v81
	s_waitcnt lgkmcnt(0)
	ds_read_b128 v[216:219], v159 offset:0
	ds_read_b128 v[220:223], v159 offset:32
	ds_read_b128 v[224:227], v159 offset:64
	ds_read_b128 v[228:231], v159 offset:96
	ds_read_b128 v[232:235], v159 offset:128
	ds_read_b128 v[236:239], v159 offset:160
	v_mfma_f32_32x32x16_bf16 v[50:65], v[160:163], v[240:243], v[50:65]
	v_add_f32_e32 v192, v82, v84
	v_add_f32_e32 v193, v83, v85
	v_add_f32_e32 v192, v86, v192
	v_add_f32_e32 v193, v87, v193
	v_mfma_f32_32x32x16_bf16 v[34:49], v[164:167], v[240:243], v[34:49]
	v_add_f32_e32 v192, v88, v192
	v_add_f32_e32 v193, v89, v193
	v_add_f32_e32 v192, v90, v192
	v_add_f32_e32 v193, v91, v193
	v_mfma_f32_32x32x16_bf16 v[50:65], v[168:171], v[244:247], v[50:65]
	v_add_f32_e32 v192, v92, v192
	v_add_f32_e32 v193, v93, v193
	v_add_f32_e32 v192, v94, v192
	v_add_f32_e32 v193, v95, v193
	v_mfma_f32_32x32x16_bf16 v[34:49], v[172:175], v[244:247], v[34:49]
	v_add_f32_e32 v192, v96, v192
	v_add_f32_e32 v193, v97, v193
	v_add_f32_e32 v192, v192, v193
	v_add_f32_e32 v215, v215, v192
	s_cmp_lt_u32 s2, s65
	s_cbranch_scc0 .Laa_nostage0
	s_waitcnt vmcnt(1)
	s_add_i32 s52, s19, 0x0
	v_add_u32_e32 v203, s52, v142
	v_add_u32_e32 v203, 0x3400, v203
	ds_write2_b64 v203, v[130:131], v[132:133] offset1:1
	s_and_saveexec_b64 vcc, s[44:45]
	v_add_u32_e32 v203, s52, v140
	ds_write_b128 v203, v[122:125]
	s_or_b64 exec, exec, vcc
	s_and_saveexec_b64 vcc, s[46:47]
	v_add_u32_e32 v203, s52, v141
	ds_write_b128 v203, v[126:129]
	s_or_b64 exec, exec, vcc
; template <int DQK, bool STATIC>
; DI void attn_item8(const bf16_t* __restrict__ Q, const bf16_t* __restrict__ Kp, const bf16_t* __restrict__ Vt, int nkeys, char* lds,
;                   const bf16_t* __restrict__ Pg, bf16_t* __restrict__ Yg  , float mfix) {
;     ...
; #pragma unroll
;     for (int ks = 0; ks < NQS; ++ks) s1 = MFMA32(kf[1][ks], qf[ks], s1);
;     {
;       float ps = 0.f;
; #pragma unroll
;       for (int e = 0; e < 16; ++e) { float p = STATIC ? __builtin_amdgcn_exp2f(s0[e]) : __builtin_amdgcn_exp2f(s0[e] - m_run); s0[e] = p; ps += p; }
;       l_run += ps;
;     }
;     if (!STATIC) {
;       float mx = s1[0];
; #pragma unroll
;       for (int e = 1; e < 16; ++e) mx = fmaxf(mx, s1[e]);
;       mx = fmaxf(mx, __shfl_xor(mx, 32));
;       if (!__all(mx <= m_run + 8.f)) {
;         const float m_new = fmaxf(m_run, mx);
;         const float alpha = __builtin_amdgcn_exp2f(m_run - m_new);
;         m_run = m_new; l_run *= alpha;
; #pragma unroll
;         for (int e = 0; e < 16; ++e) s0[e] *= alpha;
; #pragma unroll
;         for (int d = 0; d < 2; ++d)
; #pragma unroll
;           for (int e = 0; e < 16; ++e) o[d][e] *= alpha;
;       }
;     }
; #pragma unroll
;     for (int s2 = 0; s2 < 2; ++s2) {
;       u32x4 pw = {cvtpk(s0[8 * s2], s0[8 * s2 + 1]), cvtpk(s0[8 * s2 + 2], s0[8 * s2 + 3]), cvtpk(s0[8 * s2 + 4], s0[8 * s2 + 5]), cvtpk(s0[8 * s2 + 6], s0[8 * s2 + 7])};
;       bf16x8 pf = __builtin_bit_cast(bf16x8, pw);
; #pragma unroll
;       for (int d = 0; d < 2; ++d) o[d] = MFMA32(__builtin_bit_cast(bf16x8, vw[0][s2][d]), pf, o[d]);
;     }
;     {
;       float ps = 0.f;
; #pragma unroll
;       for (int e = 0; e < 16; ++e) { float p = STATIC ? __builtin_amdgcn_exp2f(s1[e]) : __builtin_amdgcn_exp2f(s1[e] - m_run); s1[e] = p; ps += p; }
;       l_run += ps;
;     }
; #pragma unroll
;     for (int s2 = 0; s2 < 2; ++s2) {
;       u32x4 pw = {cvtpk(s1[8 * s2], s1[8 * s2 + 1]), cvtpk(s1[8 * s2 + 2], s1[8 * s2 + 3]), cvtpk(s1[8 * s2 + 4], s1[8 * s2 + 5]), cvtpk(s1[8 * s2 + 6], s1[8 * s2 + 7])};
;       bf16x8 pf = __builtin_bit_cast(bf16x8, pw);
; #pragma unroll
;       for (int d = 0; d < 2; ++d) o[d] = MFMA32(__builtin_bit_cast(bf16x8, vw[1][s2][d]), pf, o[d]);
;     }
;     if (more) {
;       char* nxt = nxtp + sub * BUF;
; #pragma unroll
;       for (int i = 0; i < NKC; ++i) if (koffl[i] >= 0) *(u32x4*)(nxt + koffl[i]) = rk[i];
; #pragma unroll
.Laa_nostage0:
	ds_read_b128 v[160:163], v159 offset:6656
	ds_read_b128 v[164:167], v159 offset:6688
	ds_read_b128 v[168:171], v159 offset:6720
	ds_read_b128 v[172:175], v159 offset:6752
	ds_read_b128 v[176:179], v159 offset:6784
	ds_read_b128 v[180:183], v159 offset:6816
	s_waitcnt lgkmcnt(6)
	v_mfma_f32_32x32x16_bf16 v[82:97], v[216:219], v[118:121], v[18:33]
	v_add_f32_e32 v192, v66, v68
	v_add_f32_e32 v193, v67, v69
	v_mfma_f32_32x32x16_bf16 v[82:97], v[220:223], v[98:101], v[82:97]
	v_add_f32_e32 v192, v70, v192
	v_add_f32_e32 v193, v71, v193
	v_mfma_f32_32x32x16_bf16 v[82:97], v[224:227], v[102:105], v[82:97]
	v_add_f32_e32 v192, v72, v192
	v_add_f32_e32 v193, v73, v193
	v_mfma_f32_32x32x16_bf16 v[82:97], v[228:231], v[106:109], v[82:97]
	v_add_f32_e32 v192, v74, v192
	v_add_f32_e32 v193, v75, v193
	v_mfma_f32_32x32x16_bf16 v[82:97], v[232:235], v[110:113], v[82:97]
	v_add_f32_e32 v192, v76, v192
	v_add_f32_e32 v193, v77, v193
	v_mfma_f32_32x32x16_bf16 v[82:97], v[236:239], v[114:117], v[82:97]
	v_add_f32_e32 v192, v78, v192
	v_add_f32_e32 v193, v79, v193
	v_add_f32_e32 v192, v80, v192
	v_add_f32_e32 v193, v81, v193
	v_add_f32_e32 v192, v192, v193
	v_add_f32_e32 v215, v215, v192
	s_waitcnt lgkmcnt(0)
	ds_read2_b64 v[216:219], v185 offset0:128 offset1:130
	ds_read2_b64 v[220:223], v191 offset0:160 offset1:162
	ds_read2_b64 v[224:227], v185 offset0:132 offset1:134
	ds_read2_b64 v[228:231], v191 offset0:164 offset1:166
	v_mfma_f32_32x32x16_bf16 v[66:81], v[160:163], v[118:121], v[18:33]
	v_exp_f32_e32 v82, v82
	v_exp_f32_e32 v83, v83
	v_mfma_f32_32x32x16_bf16 v[66:81], v[164:167], v[98:101], v[66:81]
	v_exp_f32_e32 v84, v84
	v_exp_f32_e32 v85, v85
	v_exp_f32_e32 v86, v86
	v_mfma_f32_32x32x16_bf16 v[66:81], v[168:171], v[102:105], v[66:81]
	v_exp_f32_e32 v87, v87
	v_exp_f32_e32 v88, v88
	v_exp_f32_e32 v89, v89
	v_mfma_f32_32x32x16_bf16 v[66:81], v[172:175], v[106:109], v[66:81]
	v_exp_f32_e32 v90, v90
	v_exp_f32_e32 v91, v91
	v_exp_f32_e32 v92, v92
	v_mfma_f32_32x32x16_bf16 v[66:81], v[176:179], v[110:113], v[66:81]
	v_exp_f32_e32 v93, v93
	v_exp_f32_e32 v94, v94
	v_exp_f32_e32 v95, v95
	v_mfma_f32_32x32x16_bf16 v[66:81], v[180:183], v[114:117], v[66:81]
	v_exp_f32_e32 v96, v96
	v_exp_f32_e32 v97, v97
	v_cvt_pk_bf16_f32 v240, v82, v83
	v_cvt_pk_bf16_f32 v241, v84, v85
	v_cvt_pk_bf16_f32 v242, v86, v87
	v_cvt_pk_bf16_f32 v243, v88, v89
	v_cvt_pk_bf16_f32 v244, v90, v91
	v_cvt_pk_bf16_f32 v245, v92, v93
	v_cvt_pk_bf16_f32 v246, v94, v95
	v_cvt_pk_bf16_f32 v247, v96, v97
	s_waitcnt lgkmcnt(0)
	ds_read2_b64 v[160:163], v185 offset0:136 offset1:138
	ds_read2_b64 v[164:167], v191 offset0:168 offset1:170
	ds_read2_b64 v[168:171], v185 offset0:140 offset1:142
	ds_read2_b64 v[172:175], v191 offset0:172 offset1:174
	v_mfma_f32_32x32x16_bf16 v[50:65], v[216:219], v[240:243], v[50:65]
	v_exp_f32_e32 v66, v66
	v_exp_f32_e32 v67, v67
	v_exp_f32_e32 v68, v68
	v_exp_f32_e32 v69, v69
	v_mfma_f32_32x32x16_bf16 v[34:49], v[220:223], v[240:243], v[34:49]
	v_exp_f32_e32 v70, v70
	v_exp_f32_e32 v71, v71
	v_exp_f32_e32 v72, v72
	v_exp_f32_e32 v73, v73
	v_mfma_f32_32x32x16_bf16 v[50:65], v[224:227], v[244:247], v[50:65]
	v_exp_f32_e32 v74, v74
	v_exp_f32_e32 v75, v75
	v_exp_f32_e32 v76, v76
	v_exp_f32_e32 v77, v77
	v_mfma_f32_32x32x16_bf16 v[34:49], v[228:231], v[244:247], v[34:49]
	v_exp_f32_e32 v78, v78
	v_exp_f32_e32 v79, v79
	v_exp_f32_e32 v80, v80
	v_exp_f32_e32 v81, v81
	v_cvt_pk_bf16_f32 v240, v66, v67
	v_cvt_pk_bf16_f32 v241, v68, v69
	v_cvt_pk_bf16_f32 v242, v70, v71
	v_cvt_pk_bf16_f32 v243, v72, v73
	v_cvt_pk_bf16_f32 v244, v74, v75
	v_cvt_pk_bf16_f32 v245, v76, v77
	v_cvt_pk_bf16_f32 v246, v78, v79
	v_cvt_pk_bf16_f32 v247, v80, v81
	s_waitcnt lgkmcnt(0)
	v_mfma_f32_32x32x16_bf16 v[50:65], v[160:163], v[240:243], v[50:65]
	v_add_f32_e32 v192, v82, v84
	v_add_f32_e32 v193, v83, v85
	v_add_f32_e32 v192, v86, v192
	v_add_f32_e32 v193, v87, v193
	v_mfma_f32_32x32x16_bf16 v[34:49], v[164:167], v[240:243], v[34:49]
	v_add_f32_e32 v192, v88, v192
	v_add_f32_e32 v193, v89, v193
	v_add_f32_e32 v192, v90, v192
	v_add_f32_e32 v193, v91, v193
	v_mfma_f32_32x32x16_bf16 v[50:65], v[168:171], v[244:247], v[50:65]
	v_add_f32_e32 v192, v92, v192
	v_add_f32_e32 v193, v93, v193
	v_add_f32_e32 v192, v94, v192
	v_add_f32_e32 v193, v95, v193
	v_mfma_f32_32x32x16_bf16 v[34:49], v[172:175], v[244:247], v[34:49]
	v_add_f32_e32 v192, v96, v192
	v_add_f32_e32 v193, v97, v193
	v_add_f32_e32 v192, v192, v193
	v_add_f32_e32 v215, v215, v192
	s_cmp_lt_u32 s2, s65
	s_cbranch_scc0 .Laa_nostage1
	s_waitcnt vmcnt(0)
	s_add_i32 s52, s19, 0x5600
	v_add_u32_e32 v203, s52, v142
	v_add_u32_e32 v203, 0x3400, v203
	ds_write2_b64 v203, v[154:155], v[156:157] offset1:1
	s_and_saveexec_b64 vcc, s[44:45]
	v_add_u32_e32 v203, s52, v140
	ds_write_b128 v203, v[146:149]
	s_or_b64 exec, exec, vcc
	s_and_saveexec_b64 vcc, s[46:47]
	v_add_u32_e32 v203, s52, v141
	ds_write_b128 v203, v[150:153]
	s_or_b64 exec, exec, vcc
.Laa_nostage1:
.Laa_pairend:
	s_cmp_eq_u32 s2, s65
	s_waitcnt lgkmcnt(0)
	s_barrier
	s_cbranch_scc0 .LBB0_87
	v_add_f32_e32 v192, v66, v68
	v_add_f32_e32 v193, v67, v69
	v_add_f32_e32 v192, v70, v192
	v_add_f32_e32 v193, v71, v193
	v_add_f32_e32 v192, v72, v192
	v_add_f32_e32 v193, v73, v193
	v_add_f32_e32 v192, v74, v192
	v_add_f32_e32 v193, v75, v193
	v_add_f32_e32 v192, v76, v192
	v_add_f32_e32 v193, v77, v193
	v_add_f32_e32 v192, v78, v192
	v_add_f32_e32 v193, v79, v193
	v_add_f32_e32 v192, v80, v192
	v_add_f32_e32 v193, v81, v193
	v_add_f32_e32 v192, v192, v193
	v_add_f32_e32 v215, v215, v192
	s_nop 7
	s_setprio 0

; DI u32x2 pack4(f32x4 v) { u32x2 r = {cvtpk(v[0], v[1]), cvtpk(v[2], v[3])}; return r; }
; DI void phase_mix(KP p, int l, char* lds) {
;     ...
;       gemm_tile(Ap, K, Bp, K, K, lds, [&](int m, int n, f32x4 v) {
;         f32x4 o = {v[0] * sc, v[1] * sc, v[2] * sc, v[3] * sc};
;         *(u32x2*)(yo + (size_t)m * 256 + n) = pack4(o); });
;       asm volatile("s_waitcnt vmcnt(0)" ::: "memory");
;       __syncthreads();
;       if (tid0 == 0) {
;         __builtin_amdgcn_fence(__ATOMIC_RELEASE, "agent");
;         asm volatile("s_waitcnt vmcnt(0)" ::: "memory");
;         __hip_atomic_fetch_add(&cnt[b * 18 + (isl ? mt : 16 + mt)], 1u, __ATOMIC_RELAXED, __HIP_MEMORY_SCOPE_AGENT);
;       }
.LBB0_177:
	ds_read_b128 v[4:7], v0
	v_lshl_add_u64 v[8:9], v[2:3], 0, s[50:51]
	s_mov_b32 s2, 0x14f76000
	s_add_u32 s50, s50, 0x4000
	s_addc_u32 s51, s51, 0
	s_waitcnt lgkmcnt(0)
	v_pk_mul_f32 v[4:5], s[40:41], v[4:5]
	v_pk_mul_f32 v[6:7], s[40:41], v[6:7]
	v_cvt_pk_bf16_f32 v4, v4, v5
	v_cvt_pk_bf16_f32 v5, v6, v7
	v_add_co_u32_e32 v6, vcc, 0x14f75000, v8
	s_cmp_lg_u32 s50, 0x10000
	s_nop 0
	v_addc_co_u32_e32 v7, vcc, 0, v9, vcc
	global_store_dwordx2 v[6:7], v[4:5], off offset:256 sc0 sc1
	ds_read_b128 v[4:7], v0 offset:4224
	s_waitcnt lgkmcnt(0)
	v_pk_mul_f32 v[4:5], s[40:41], v[4:5]
	v_pk_mul_f32 v[6:7], s[40:41], v[6:7]
	v_cvt_pk_bf16_f32 v4, v4, v5
	v_cvt_pk_bf16_f32 v5, v6, v7
	v_add_co_u32_e32 v6, vcc, s2, v8
	s_mov_b32 s2, 0x14f77000
	s_nop 0
	v_addc_co_u32_e32 v7, vcc, 0, v9, vcc
	global_store_dwordx2 v[6:7], v[4:5], off offset:256 sc0 sc1
	ds_read_b128 v[4:7], v0 offset:8448
	s_waitcnt lgkmcnt(0)
	v_pk_mul_f32 v[4:5], s[40:41], v[4:5]
	v_pk_mul_f32 v[6:7], s[40:41], v[6:7]
	v_cvt_pk_bf16_f32 v4, v4, v5
	v_cvt_pk_bf16_f32 v5, v6, v7
	v_add_co_u32_e32 v6, vcc, s2, v8
	s_mov_b32 s2, 0x14f78000
	s_nop 0
	v_addc_co_u32_e32 v7, vcc, 0, v9, vcc
	global_store_dwordx2 v[6:7], v[4:5], off offset:256 sc0 sc1
	ds_read_b128 v[4:7], v0 offset:12672
	v_add_u32_e32 v0, 0x4200, v0
	s_waitcnt lgkmcnt(0)
	v_pk_mul_f32 v[4:5], s[40:41], v[4:5]
	v_pk_mul_f32 v[6:7], s[40:41], v[6:7]
	v_cvt_pk_bf16_f32 v4, v4, v5
	v_cvt_pk_bf16_f32 v5, v6, v7
	v_add_co_u32_e32 v6, vcc, s2, v8
	s_nop 1
	v_addc_co_u32_e32 v7, vcc, 0, v9, vcc
	global_store_dwordx2 v[6:7], v[4:5], off offset:256 sc0 sc1
	s_cbranch_scc1 .LBB0_177
	s_waitcnt lgkmcnt(0)
	s_barrier
	s_waitcnt vmcnt(0)
	s_barrier
	s_and_saveexec_b64 s[18:19], s[64:65]
	s_cbranch_execz .LBB0_125
	s_or_b32 s20, s34, 16
	s_mul_i32 s2, s4, 18
	s_and_b64 s[4:5], s[36:37], exec
	s_cselect_b32 s4, s34, s20
	s_add_i32 s4, s2, s4
	s_ashr_i32 s5, s4, 31
	s_lshl_b64 s[4:5], s[4:5], 2
	v_readlane_b32 s2, v255, 43
	s_add_u32 s4, s2, s4
	v_readlane_b32 s2, v255, 44
	s_addc_u32 s5, s2, s5
	s_waitcnt vmcnt(0)
	v_mov_b64_e32 v[2:3], s[4:5]
	global_atomic_add v[2:3], v197, off
	s_branch .LBB0_125
